# stash stores and loads marked nt (written once, read once) on top of the coalesced stash layout
# baseline (speedup 1.0000x reference)
.LBB0_356:
	v_readfirstlane_b32 s96, v158
	v_readfirstlane_b32 s97, v159
	v_and_b32_e32 v254, 63, v162
	v_lshlrev_b32_e32 v254, 4, v254
	s_add_u32 s98, s96, 0x3000
	s_addc_u32 s99, s97, 0
	s_add_u32 s96, s96, 0x1000
	s_addc_u32 s97, s97, 0
	v_mov_b32_e32 v218, v68
	v_mov_b32_e32 v216, v163
	v_ashrrev_i32_e32 v217, 31, v163
	v_lshl_add_u64 v[216:217], v[216:217], 2, s[38:39]
	global_load_dword v204, v[216:217], off
	global_load_dword v205, v[216:217], off offset:128
	global_load_dword v206, v[216:217], off offset:256
	global_load_dword v207, v[216:217], off offset:384
	global_load_dwordx4 v[106:109], v254, s[96:97] offset:-4096 nt
	global_load_dwordx4 v[110:113], v254, s[96:97] offset:-3072 nt
	global_load_dwordx4 v[114:117], v254, s[96:97] offset:-2048 nt
	global_load_dwordx4 v[118:121], v254, s[96:97] offset:-1024 nt
	global_load_dwordx4 v[122:125], v254, s[96:97] offset:0 nt
	global_load_dwordx4 v[126:129], v254, s[96:97] offset:1024 nt
	global_load_dwordx4 v[130:133], v254, s[96:97] offset:2048 nt
	global_load_dwordx4 v[134:137], v254, s[96:97] offset:3072 nt
	global_load_dwordx4 v[138:141], v254, s[98:99] offset:-4096 nt
	global_load_dwordx4 v[142:145], v254, s[98:99] offset:-3072 nt
	global_load_dwordx4 v[146:149], v254, s[98:99] offset:-2048 nt
	global_load_dwordx4 v[150:153], v254, s[98:99] offset:-1024 nt
	global_load_dwordx4 v[154:157], v254, s[98:99] offset:0 nt
	global_load_dwordx4 v[176:179], v254, s[98:99] offset:1024 nt
	global_load_dwordx4 v[180:183], v254, s[98:99] offset:2048 nt
	global_load_dwordx4 v[184:187], v254, s[98:99] offset:3072 nt
	ds_read_b128 v[66:69], v218
	ds_read_b128 v[70:73], v218 offset:32
	ds_read_b128 v[74:77], v218 offset:64
	ds_read_b128 v[78:81], v218 offset:96
	s_add_u32 s100, s92, s20
	s_addc_u32 s101, s93, s21
	s_add_u32 s100, s100, 0x2e400000
	s_addc_u32 s101, s101, 0
	v_xor_b32_e32 v208, 16, v174
	v_lshlrev_b32_e32 v208, 2, v208
	s_waitcnt lgkmcnt(0)
	v_rcp_f32_e32 v66, v66
	v_rcp_f32_e32 v67, v67
	v_rcp_f32_e32 v68, v68
	v_rcp_f32_e32 v69, v69
	v_rcp_f32_e32 v70, v70
	v_rcp_f32_e32 v71, v71
	v_rcp_f32_e32 v72, v72
	v_rcp_f32_e32 v73, v73
	v_rcp_f32_e32 v74, v74
	v_rcp_f32_e32 v75, v75
	v_rcp_f32_e32 v76, v76
	v_rcp_f32_e32 v77, v77
	v_rcp_f32_e32 v78, v78
	v_rcp_f32_e32 v79, v79
	v_rcp_f32_e32 v80, v80
	v_rcp_f32_e32 v81, v81
	v_mul_f32_e32 v66, v1, v66
	v_mul_f32_e32 v67, v1, v67
	v_mul_f32_e32 v68, v1, v68
	v_mul_f32_e32 v69, v1, v69
	v_mul_f32_e32 v70, v1, v70
	v_mul_f32_e32 v71, v1, v71
	v_mul_f32_e32 v72, v1, v72
	v_mul_f32_e32 v73, v1, v73
	v_mul_f32_e32 v74, v1, v74
	v_mul_f32_e32 v75, v1, v75
	v_mul_f32_e32 v76, v1, v76
	v_mul_f32_e32 v77, v1, v77
	v_mul_f32_e32 v78, v1, v78
	v_mul_f32_e32 v79, v1, v79
	v_mul_f32_e32 v80, v1, v80
	v_mul_f32_e32 v81, v1, v81
	s_waitcnt vmcnt(15)
	v_fma_f32 v106, -v50, v66, v106
	v_fma_f32 v107, -v34, v66, v107
	v_fma_f32 v108, -v18, v66, v108
	v_fma_f32 v109, -v2, v66, v109
	v_mul_f32_e32 v204, 0x3f4ccccd, v204
	v_mul_f32_e32 v205, 0x3f4ccccd, v205
	v_mul_f32_e32 v206, 0x3f4ccccd, v206
	v_mul_f32_e32 v207, 0x3f4ccccd, v207
	v_mul_f32_e32 v66, v106, v106
	v_fmac_f32_e32 v66, v107, v107
	v_fmac_f32_e32 v66, v108, v108
	v_fmac_f32_e32 v66, v109, v109
	s_waitcnt vmcnt(14)
	v_fma_f32 v110, -v51, v67, v110
	v_fma_f32 v111, -v35, v67, v111
	v_fma_f32 v112, -v19, v67, v112
	v_fma_f32 v113, -v3, v67, v113
	v_mul_f32_e32 v67, v110, v110
	v_fmac_f32_e32 v67, v111, v111
	v_fmac_f32_e32 v67, v112, v112
	v_fmac_f32_e32 v67, v113, v113
	s_waitcnt vmcnt(13)
	v_fma_f32 v114, -v52, v68, v114
	v_fma_f32 v115, -v36, v68, v115
	v_fma_f32 v116, -v20, v68, v116
	v_fma_f32 v117, -v4, v68, v117
	v_mul_f32_e32 v68, v114, v114
	v_fmac_f32_e32 v68, v115, v115
	v_fmac_f32_e32 v68, v116, v116
	v_fmac_f32_e32 v68, v117, v117
	s_waitcnt vmcnt(12)
	v_fma_f32 v118, -v53, v69, v118
	v_fma_f32 v119, -v37, v69, v119
	v_fma_f32 v120, -v21, v69, v120
	v_fma_f32 v121, -v5, v69, v121
	v_mul_f32_e32 v69, v118, v118
	v_fmac_f32_e32 v69, v119, v119
	v_fmac_f32_e32 v69, v120, v120
	v_fmac_f32_e32 v69, v121, v121
	s_waitcnt vmcnt(11)
	v_fma_f32 v122, -v54, v70, v122
	v_fma_f32 v123, -v38, v70, v123
	v_fma_f32 v124, -v22, v70, v124
	v_fma_f32 v125, -v6, v70, v125
	v_mul_f32_e32 v70, v122, v122
	v_fmac_f32_e32 v70, v123, v123
	v_fmac_f32_e32 v70, v124, v124
	v_fmac_f32_e32 v70, v125, v125
	s_waitcnt vmcnt(10)
	v_fma_f32 v126, -v55, v71, v126
	v_fma_f32 v127, -v39, v71, v127
	v_fma_f32 v128, -v23, v71, v128
	v_fma_f32 v129, -v7, v71, v129
	v_mul_f32_e32 v71, v126, v126
	v_fmac_f32_e32 v71, v127, v127
	v_fmac_f32_e32 v71, v128, v128
	v_fmac_f32_e32 v71, v129, v129
	s_waitcnt vmcnt(9)
	v_fma_f32 v130, -v56, v72, v130
	v_fma_f32 v131, -v40, v72, v131
	v_fma_f32 v132, -v24, v72, v132
	v_fma_f32 v133, -v8, v72, v133
	v_mul_f32_e32 v72, v130, v130
	v_fmac_f32_e32 v72, v131, v131
	v_fmac_f32_e32 v72, v132, v132
	v_fmac_f32_e32 v72, v133, v133
	s_waitcnt vmcnt(8)
	v_fma_f32 v134, -v57, v73, v134
	v_fma_f32 v135, -v41, v73, v135
	v_fma_f32 v136, -v25, v73, v136
	v_fma_f32 v137, -v9, v73, v137
	v_mul_f32_e32 v73, v134, v134
	v_fmac_f32_e32 v73, v135, v135
	v_fmac_f32_e32 v73, v136, v136
	v_fmac_f32_e32 v73, v137, v137
	s_waitcnt vmcnt(7)
	v_fma_f32 v138, -v58, v74, v138
	v_fma_f32 v139, -v42, v74, v139
	v_fma_f32 v140, -v26, v74, v140
	v_fma_f32 v141, -v10, v74, v141
	v_mul_f32_e32 v74, v138, v138
	v_fmac_f32_e32 v74, v139, v139
	v_fmac_f32_e32 v74, v140, v140
	v_fmac_f32_e32 v74, v141, v141
	s_waitcnt vmcnt(6)
	v_fma_f32 v142, -v59, v75, v142
	v_fma_f32 v143, -v43, v75, v143
	v_fma_f32 v144, -v27, v75, v144
	v_fma_f32 v145, -v11, v75, v145
	v_mul_f32_e32 v75, v142, v142
	v_fmac_f32_e32 v75, v143, v143
	v_fmac_f32_e32 v75, v144, v144
	v_fmac_f32_e32 v75, v145, v145
	s_waitcnt vmcnt(5)
	v_fma_f32 v146, -v60, v76, v146
	v_fma_f32 v147, -v44, v76, v147
	v_fma_f32 v148, -v28, v76, v148
	v_fma_f32 v149, -v12, v76, v149
	v_mul_f32_e32 v76, v146, v146
	v_fmac_f32_e32 v76, v147, v147
	v_fmac_f32_e32 v76, v148, v148
	v_fmac_f32_e32 v76, v149, v149
	s_waitcnt vmcnt(4)
	v_fma_f32 v150, -v61, v77, v150
	v_fma_f32 v151, -v45, v77, v151
	v_fma_f32 v152, -v29, v77, v152
	v_fma_f32 v153, -v13, v77, v153
	v_mul_f32_e32 v77, v150, v150
	v_fmac_f32_e32 v77, v151, v151
	v_fmac_f32_e32 v77, v152, v152
	v_fmac_f32_e32 v77, v153, v153
	s_waitcnt vmcnt(3)
	v_fma_f32 v154, -v62, v78, v154
	v_fma_f32 v155, -v46, v78, v155
	v_fma_f32 v156, -v30, v78, v156
	v_fma_f32 v157, -v14, v78, v157
	v_mul_f32_e32 v78, v154, v154
	v_fmac_f32_e32 v78, v155, v155
	v_fmac_f32_e32 v78, v156, v156
	v_fmac_f32_e32 v78, v157, v157
	s_waitcnt vmcnt(2)
	v_fma_f32 v176, -v63, v79, v176
	v_fma_f32 v177, -v47, v79, v177
	v_fma_f32 v178, -v31, v79, v178
	v_fma_f32 v179, -v15, v79, v179
	v_mul_f32_e32 v79, v176, v176
	v_fmac_f32_e32 v79, v177, v177
	v_fmac_f32_e32 v79, v178, v178
	v_fmac_f32_e32 v79, v179, v179
	s_waitcnt vmcnt(1)
	v_fma_f32 v180, -v64, v80, v180
	v_fma_f32 v181, -v48, v80, v181
	v_fma_f32 v182, -v32, v80, v182
	v_fma_f32 v183, -v16, v80, v183
	v_mul_f32_e32 v80, v180, v180
	v_fmac_f32_e32 v80, v181, v181
	v_fmac_f32_e32 v80, v182, v182
	v_fmac_f32_e32 v80, v183, v183
	s_waitcnt vmcnt(0)
	v_fma_f32 v184, -v65, v81, v184
	v_fma_f32 v185, -v49, v81, v185
	v_fma_f32 v186, -v33, v81, v186
	v_fma_f32 v187, -v17, v81, v187
	v_mul_f32_e32 v81, v184, v184
	v_fmac_f32_e32 v81, v185, v185
	v_fmac_f32_e32 v81, v186, v186
	v_fmac_f32_e32 v81, v187, v187
	v_add_f32_dpp v66, v66, v66 quad_perm:[1,0,3,2] row_mask:0xf bank_mask:0xf
	v_add_f32_dpp v67, v67, v67 quad_perm:[1,0,3,2] row_mask:0xf bank_mask:0xf
	v_add_f32_dpp v68, v68, v68 quad_perm:[1,0,3,2] row_mask:0xf bank_mask:0xf
	v_add_f32_dpp v69, v69, v69 quad_perm:[1,0,3,2] row_mask:0xf bank_mask:0xf
	v_add_f32_dpp v70, v70, v70 quad_perm:[1,0,3,2] row_mask:0xf bank_mask:0xf
	v_add_f32_dpp v71, v71, v71 quad_perm:[1,0,3,2] row_mask:0xf bank_mask:0xf
	v_add_f32_dpp v72, v72, v72 quad_perm:[1,0,3,2] row_mask:0xf bank_mask:0xf
	v_add_f32_dpp v73, v73, v73 quad_perm:[1,0,3,2] row_mask:0xf bank_mask:0xf
	v_add_f32_dpp v74, v74, v74 quad_perm:[1,0,3,2] row_mask:0xf bank_mask:0xf
	v_add_f32_dpp v75, v75, v75 quad_perm:[1,0,3,2] row_mask:0xf bank_mask:0xf
	v_add_f32_dpp v76, v76, v76 quad_perm:[1,0,3,2] row_mask:0xf bank_mask:0xf
	v_add_f32_dpp v77, v77, v77 quad_perm:[1,0,3,2] row_mask:0xf bank_mask:0xf
	v_add_f32_dpp v78, v78, v78 quad_perm:[1,0,3,2] row_mask:0xf bank_mask:0xf
	v_add_f32_dpp v79, v79, v79 quad_perm:[1,0,3,2] row_mask:0xf bank_mask:0xf
	v_add_f32_dpp v80, v80, v80 quad_perm:[1,0,3,2] row_mask:0xf bank_mask:0xf
	v_add_f32_dpp v81, v81, v81 quad_perm:[1,0,3,2] row_mask:0xf bank_mask:0xf
	v_add_f32_dpp v66, v66, v66 quad_perm:[2,3,0,1] row_mask:0xf bank_mask:0xf
	v_add_f32_dpp v67, v67, v67 quad_perm:[2,3,0,1] row_mask:0xf bank_mask:0xf
	v_add_f32_dpp v68, v68, v68 quad_perm:[2,3,0,1] row_mask:0xf bank_mask:0xf
	v_add_f32_dpp v69, v69, v69 quad_perm:[2,3,0,1] row_mask:0xf bank_mask:0xf
	v_add_f32_dpp v70, v70, v70 quad_perm:[2,3,0,1] row_mask:0xf bank_mask:0xf
	v_add_f32_dpp v71, v71, v71 quad_perm:[2,3,0,1] row_mask:0xf bank_mask:0xf
	v_add_f32_dpp v72, v72, v72 quad_perm:[2,3,0,1] row_mask:0xf bank_mask:0xf
	v_add_f32_dpp v73, v73, v73 quad_perm:[2,3,0,1] row_mask:0xf bank_mask:0xf
	v_add_f32_dpp v74, v74, v74 quad_perm:[2,3,0,1] row_mask:0xf bank_mask:0xf
	v_add_f32_dpp v75, v75, v75 quad_perm:[2,3,0,1] row_mask:0xf bank_mask:0xf
	v_add_f32_dpp v76, v76, v76 quad_perm:[2,3,0,1] row_mask:0xf bank_mask:0xf
	v_add_f32_dpp v77, v77, v77 quad_perm:[2,3,0,1] row_mask:0xf bank_mask:0xf
	v_add_f32_dpp v78, v78, v78 quad_perm:[2,3,0,1] row_mask:0xf bank_mask:0xf
	v_add_f32_dpp v79, v79, v79 quad_perm:[2,3,0,1] row_mask:0xf bank_mask:0xf
	v_add_f32_dpp v80, v80, v80 quad_perm:[2,3,0,1] row_mask:0xf bank_mask:0xf
	v_add_f32_dpp v81, v81, v81 quad_perm:[2,3,0,1] row_mask:0xf bank_mask:0xf
	v_add_f32_dpp v66, v66, v66 row_half_mirror row_mask:0xf bank_mask:0xf
	v_add_f32_dpp v67, v67, v67 row_half_mirror row_mask:0xf bank_mask:0xf
	v_add_f32_dpp v68, v68, v68 row_half_mirror row_mask:0xf bank_mask:0xf
	v_add_f32_dpp v69, v69, v69 row_half_mirror row_mask:0xf bank_mask:0xf
	v_add_f32_dpp v70, v70, v70 row_half_mirror row_mask:0xf bank_mask:0xf
	v_add_f32_dpp v71, v71, v71 row_half_mirror row_mask:0xf bank_mask:0xf
	v_add_f32_dpp v72, v72, v72 row_half_mirror row_mask:0xf bank_mask:0xf
	v_add_f32_dpp v73, v73, v73 row_half_mirror row_mask:0xf bank_mask:0xf
	v_add_f32_dpp v74, v74, v74 row_half_mirror row_mask:0xf bank_mask:0xf
	v_add_f32_dpp v75, v75, v75 row_half_mirror row_mask:0xf bank_mask:0xf
	v_add_f32_dpp v76, v76, v76 row_half_mirror row_mask:0xf bank_mask:0xf
	v_add_f32_dpp v77, v77, v77 row_half_mirror row_mask:0xf bank_mask:0xf
	v_add_f32_dpp v78, v78, v78 row_half_mirror row_mask:0xf bank_mask:0xf
	v_add_f32_dpp v79, v79, v79 row_half_mirror row_mask:0xf bank_mask:0xf
	v_add_f32_dpp v80, v80, v80 row_half_mirror row_mask:0xf bank_mask:0xf
	v_add_f32_dpp v81, v81, v81 row_half_mirror row_mask:0xf bank_mask:0xf
	v_add_f32_dpp v66, v66, v66 row_mirror row_mask:0xf bank_mask:0xf
	v_add_f32_dpp v67, v67, v67 row_mirror row_mask:0xf bank_mask:0xf
	v_add_f32_dpp v68, v68, v68 row_mirror row_mask:0xf bank_mask:0xf
	v_add_f32_dpp v69, v69, v69 row_mirror row_mask:0xf bank_mask:0xf
	v_add_f32_dpp v70, v70, v70 row_mirror row_mask:0xf bank_mask:0xf
	v_add_f32_dpp v71, v71, v71 row_mirror row_mask:0xf bank_mask:0xf
	v_add_f32_dpp v72, v72, v72 row_mirror row_mask:0xf bank_mask:0xf
	v_add_f32_dpp v73, v73, v73 row_mirror row_mask:0xf bank_mask:0xf
	v_add_f32_dpp v74, v74, v74 row_mirror row_mask:0xf bank_mask:0xf
	v_add_f32_dpp v75, v75, v75 row_mirror row_mask:0xf bank_mask:0xf
	v_add_f32_dpp v76, v76, v76 row_mirror row_mask:0xf bank_mask:0xf
	v_add_f32_dpp v77, v77, v77 row_mirror row_mask:0xf bank_mask:0xf
	v_add_f32_dpp v78, v78, v78 row_mirror row_mask:0xf bank_mask:0xf
	v_add_f32_dpp v79, v79, v79 row_mirror row_mask:0xf bank_mask:0xf
	v_add_f32_dpp v80, v80, v80 row_mirror row_mask:0xf bank_mask:0xf
	v_add_f32_dpp v81, v81, v81 row_mirror row_mask:0xf bank_mask:0xf
	ds_bpermute_b32 v188, v208, v66
	ds_bpermute_b32 v189, v208, v67
	ds_bpermute_b32 v190, v208, v68
	ds_bpermute_b32 v191, v208, v69
	ds_bpermute_b32 v192, v208, v70
	ds_bpermute_b32 v193, v208, v71
	ds_bpermute_b32 v194, v208, v72
	ds_bpermute_b32 v195, v208, v73
	ds_bpermute_b32 v196, v208, v74
	ds_bpermute_b32 v197, v208, v75
	ds_bpermute_b32 v198, v208, v76
	ds_bpermute_b32 v199, v208, v77
	ds_bpermute_b32 v200, v208, v78
	ds_bpermute_b32 v201, v208, v79
	ds_bpermute_b32 v202, v208, v80
	ds_bpermute_b32 v203, v208, v81
	s_waitcnt lgkmcnt(0)
	v_add_f32_e32 v66, v66, v188
	v_add_f32_e32 v67, v67, v189
	v_add_f32_e32 v68, v68, v190
	v_add_f32_e32 v69, v69, v191
	v_add_f32_e32 v70, v70, v192
	v_add_f32_e32 v71, v71, v193
	v_add_f32_e32 v72, v72, v194
	v_add_f32_e32 v73, v73, v195
	v_add_f32_e32 v74, v74, v196
	v_add_f32_e32 v75, v75, v197
	v_add_f32_e32 v76, v76, v198
	v_add_f32_e32 v77, v77, v199
	v_add_f32_e32 v78, v78, v200
	v_add_f32_e32 v79, v79, v201
	v_add_f32_e32 v80, v80, v202
	v_add_f32_e32 v81, v81, v203
	v_fmamk_f32 v66, v66, 0x3c000000, v172
	v_fmamk_f32 v67, v67, 0x3c000000, v172
	v_fmamk_f32 v68, v68, 0x3c000000, v172
	v_fmamk_f32 v69, v69, 0x3c000000, v172
	v_fmamk_f32 v70, v70, 0x3c000000, v172
	v_fmamk_f32 v71, v71, 0x3c000000, v172
	v_fmamk_f32 v72, v72, 0x3c000000, v172
	v_fmamk_f32 v73, v73, 0x3c000000, v172
	v_fmamk_f32 v74, v74, 0x3c000000, v172
	v_fmamk_f32 v75, v75, 0x3c000000, v172
	v_fmamk_f32 v76, v76, 0x3c000000, v172
	v_fmamk_f32 v77, v77, 0x3c000000, v172
	v_fmamk_f32 v78, v78, 0x3c000000, v172
	v_fmamk_f32 v79, v79, 0x3c000000, v172
	v_fmamk_f32 v80, v80, 0x3c000000, v172
	v_fmamk_f32 v81, v81, 0x3c000000, v172
	v_rsq_f32_e32 v66, v66
	v_rsq_f32_e32 v67, v67
	v_rsq_f32_e32 v68, v68
	v_rsq_f32_e32 v69, v69
	v_rsq_f32_e32 v70, v70
	v_rsq_f32_e32 v71, v71
	v_rsq_f32_e32 v72, v72
	v_rsq_f32_e32 v73, v73
	v_rsq_f32_e32 v74, v74
	v_rsq_f32_e32 v75, v75
	v_rsq_f32_e32 v76, v76
	v_rsq_f32_e32 v77, v77
	v_rsq_f32_e32 v78, v78
	v_rsq_f32_e32 v79, v79
	v_rsq_f32_e32 v80, v80
	v_rsq_f32_e32 v81, v81
	s_nop 0
	s_mov_b32 s96, 0xaaaaaaaa
	s_mov_b32 s97, 0xaaaaaaaa
	s_mov_b32 s98, 0xcccccccc
	s_mov_b32 s99, 0xcccccccc
	v_mov_b32_e32 v202, 0x5040100
	v_mov_b32_e32 v203, 0x3020706
	v_cndmask_b32_e64 v202, v202, v203, s[96:97]
	v_and_b32_e32 v209, 3, v163
	v_lshl_add_u32 v209, v164, 2, v209
	v_add_u32_e32 v209, v175, v209
	v_lshlrev_b32_e32 v209, 12, v209
	v_lshrrev_b32_e32 v210, 2, v163
	v_lshl_add_u32 v209, v210, 3, v209
	v_mul_f32_e32 v198, v106, v66
	v_mul_f32_e32 v199, v110, v67
	v_mul_f32_e32 v200, v114, v68
	v_mul_f32_e32 v201, v118, v69
	v_mul_f32_e32 v198, v204, v198
	v_mul_f32_e32 v199, v204, v199
	v_mul_f32_e32 v200, v204, v200
	v_mul_f32_e32 v201, v204, v201
	v_cvt_pk_bf16_f32 v188, v198, v199
	v_cvt_pk_bf16_f32 v189, v200, v201
	s_nop 0
	v_mov_b32_dpp v190, v188 quad_perm:[1,0,3,2] row_mask:0xf bank_mask:0xf
	v_mov_b32_dpp v191, v189 quad_perm:[1,0,3,2] row_mask:0xf bank_mask:0xf
	v_perm_b32 v192, v190, v188, v202
	v_perm_b32 v193, v191, v189, v202
	v_cndmask_b32_e64 v194, v193, v192, s[98:99]
	s_nop 1
	v_mov_b32_dpp v195, v194 quad_perm:[2,3,0,1] row_mask:0xf bank_mask:0xf
	v_cndmask_b32_e64 v196, v192, v195, s[98:99]
	v_cndmask_b32_e64 v197, v195, v193, s[98:99]
	global_store_dwordx2 v209, v[196:197], s[100:101] offset:2048
	v_mul_f32_e32 v198, v107, v66
	v_mul_f32_e32 v199, v111, v67
	v_mul_f32_e32 v200, v115, v68
	v_mul_f32_e32 v201, v119, v69
	v_mul_f32_e32 v198, v205, v198
	v_mul_f32_e32 v199, v205, v199
	v_mul_f32_e32 v200, v205, v200
	v_mul_f32_e32 v201, v205, v201
	v_cvt_pk_bf16_f32 v188, v198, v199
	v_cvt_pk_bf16_f32 v189, v200, v201
	s_nop 0
	v_mov_b32_dpp v190, v188 quad_perm:[1,0,3,2] row_mask:0xf bank_mask:0xf
	v_mov_b32_dpp v191, v189 quad_perm:[1,0,3,2] row_mask:0xf bank_mask:0xf
	v_perm_b32 v192, v190, v188, v202
	v_perm_b32 v193, v191, v189, v202
	v_cndmask_b32_e64 v194, v193, v192, s[98:99]
	s_nop 1
	v_mov_b32_dpp v195, v194 quad_perm:[2,3,0,1] row_mask:0xf bank_mask:0xf
	v_cndmask_b32_e64 v216, v192, v195, s[98:99]
	v_cndmask_b32_e64 v217, v195, v193, s[98:99]
	global_store_dwordx2 v209, v[216:217], s[100:101] offset:2112
	v_mul_f32_e32 v198, v108, v66
	v_mul_f32_e32 v199, v112, v67
	v_mul_f32_e32 v200, v116, v68
	v_mul_f32_e32 v201, v120, v69
	v_mul_f32_e32 v198, v206, v198
	v_mul_f32_e32 v199, v206, v199
	v_mul_f32_e32 v200, v206, v200
	v_mul_f32_e32 v201, v206, v201
	v_cvt_pk_bf16_f32 v188, v198, v199
	v_cvt_pk_bf16_f32 v189, v200, v201
	s_nop 0
	v_mov_b32_dpp v190, v188 quad_perm:[1,0,3,2] row_mask:0xf bank_mask:0xf
	v_mov_b32_dpp v191, v189 quad_perm:[1,0,3,2] row_mask:0xf bank_mask:0xf
	v_perm_b32 v192, v190, v188, v202
	v_perm_b32 v193, v191, v189, v202
	v_cndmask_b32_e64 v194, v193, v192, s[98:99]
	s_nop 1
	v_mov_b32_dpp v195, v194 quad_perm:[2,3,0,1] row_mask:0xf bank_mask:0xf
	v_cndmask_b32_e64 v196, v192, v195, s[98:99]
	v_cndmask_b32_e64 v197, v195, v193, s[98:99]
	global_store_dwordx2 v209, v[196:197], s[100:101] offset:2176
	v_mul_f32_e32 v198, v109, v66
	v_mul_f32_e32 v199, v113, v67
	v_mul_f32_e32 v200, v117, v68
	v_mul_f32_e32 v201, v121, v69
	v_mul_f32_e32 v198, v207, v198
	v_mul_f32_e32 v199, v207, v199
	v_mul_f32_e32 v200, v207, v200
	v_mul_f32_e32 v201, v207, v201
	v_cvt_pk_bf16_f32 v188, v198, v199
	v_cvt_pk_bf16_f32 v189, v200, v201
	s_nop 0
	v_mov_b32_dpp v190, v188 quad_perm:[1,0,3,2] row_mask:0xf bank_mask:0xf
	v_mov_b32_dpp v191, v189 quad_perm:[1,0,3,2] row_mask:0xf bank_mask:0xf
	v_perm_b32 v192, v190, v188, v202
	v_perm_b32 v193, v191, v189, v202
	v_cndmask_b32_e64 v194, v193, v192, s[98:99]
	s_nop 1
	v_mov_b32_dpp v195, v194 quad_perm:[2,3,0,1] row_mask:0xf bank_mask:0xf
	v_cndmask_b32_e64 v216, v192, v195, s[98:99]
	v_cndmask_b32_e64 v217, v195, v193, s[98:99]
	global_store_dwordx2 v209, v[216:217], s[100:101] offset:2240
	v_add_u32_e32 v210, 0x8000, v209
	v_mul_f32_e32 v198, v122, v70
	v_mul_f32_e32 v199, v126, v71
	v_mul_f32_e32 v200, v130, v72
	v_mul_f32_e32 v201, v134, v73
	v_mul_f32_e32 v198, v204, v198
	v_mul_f32_e32 v199, v204, v199
	v_mul_f32_e32 v200, v204, v200
	v_mul_f32_e32 v201, v204, v201
	v_cvt_pk_bf16_f32 v188, v198, v199
	v_cvt_pk_bf16_f32 v189, v200, v201
	s_nop 0
	v_mov_b32_dpp v190, v188 quad_perm:[1,0,3,2] row_mask:0xf bank_mask:0xf
	v_mov_b32_dpp v191, v189 quad_perm:[1,0,3,2] row_mask:0xf bank_mask:0xf
	v_perm_b32 v192, v190, v188, v202
	v_perm_b32 v193, v191, v189, v202
	v_cndmask_b32_e64 v194, v193, v192, s[98:99]
	s_nop 1
	v_mov_b32_dpp v195, v194 quad_perm:[2,3,0,1] row_mask:0xf bank_mask:0xf
	v_cndmask_b32_e64 v196, v192, v195, s[98:99]
	v_cndmask_b32_e64 v197, v195, v193, s[98:99]
	global_store_dwordx2 v210, v[196:197], s[100:101] offset:2048
	v_mul_f32_e32 v198, v123, v70
	v_mul_f32_e32 v199, v127, v71
	v_mul_f32_e32 v200, v131, v72
	v_mul_f32_e32 v201, v135, v73
	v_mul_f32_e32 v198, v205, v198
	v_mul_f32_e32 v199, v205, v199
	v_mul_f32_e32 v200, v205, v200
	v_mul_f32_e32 v201, v205, v201
	v_cvt_pk_bf16_f32 v188, v198, v199
	v_cvt_pk_bf16_f32 v189, v200, v201
	s_nop 0
	v_mov_b32_dpp v190, v188 quad_perm:[1,0,3,2] row_mask:0xf bank_mask:0xf
	v_mov_b32_dpp v191, v189 quad_perm:[1,0,3,2] row_mask:0xf bank_mask:0xf
	v_perm_b32 v192, v190, v188, v202
	v_perm_b32 v193, v191, v189, v202
	v_cndmask_b32_e64 v194, v193, v192, s[98:99]
	s_nop 1
	v_mov_b32_dpp v195, v194 quad_perm:[2,3,0,1] row_mask:0xf bank_mask:0xf
	v_cndmask_b32_e64 v216, v192, v195, s[98:99]
	v_cndmask_b32_e64 v217, v195, v193, s[98:99]
	global_store_dwordx2 v210, v[216:217], s[100:101] offset:2112
	v_mul_f32_e32 v198, v124, v70
	v_mul_f32_e32 v199, v128, v71
	v_mul_f32_e32 v200, v132, v72
	v_mul_f32_e32 v201, v136, v73
	v_mul_f32_e32 v198, v206, v198
	v_mul_f32_e32 v199, v206, v199
	v_mul_f32_e32 v200, v206, v200
	v_mul_f32_e32 v201, v206, v201
	v_cvt_pk_bf16_f32 v188, v198, v199
	v_cvt_pk_bf16_f32 v189, v200, v201
	s_nop 0
	v_mov_b32_dpp v190, v188 quad_perm:[1,0,3,2] row_mask:0xf bank_mask:0xf
	v_mov_b32_dpp v191, v189 quad_perm:[1,0,3,2] row_mask:0xf bank_mask:0xf
	v_perm_b32 v192, v190, v188, v202
	v_perm_b32 v193, v191, v189, v202
	v_cndmask_b32_e64 v194, v193, v192, s[98:99]
	s_nop 1
	v_mov_b32_dpp v195, v194 quad_perm:[2,3,0,1] row_mask:0xf bank_mask:0xf
	v_cndmask_b32_e64 v196, v192, v195, s[98:99]
	v_cndmask_b32_e64 v197, v195, v193, s[98:99]
	global_store_dwordx2 v210, v[196:197], s[100:101] offset:2176
	v_mul_f32_e32 v198, v125, v70
	v_mul_f32_e32 v199, v129, v71
	v_mul_f32_e32 v200, v133, v72
	v_mul_f32_e32 v201, v137, v73
	v_mul_f32_e32 v198, v207, v198
	v_mul_f32_e32 v199, v207, v199
	v_mul_f32_e32 v200, v207, v200
	v_mul_f32_e32 v201, v207, v201
	v_cvt_pk_bf16_f32 v188, v198, v199
	v_cvt_pk_bf16_f32 v189, v200, v201
	s_nop 0
	v_mov_b32_dpp v190, v188 quad_perm:[1,0,3,2] row_mask:0xf bank_mask:0xf
	v_mov_b32_dpp v191, v189 quad_perm:[1,0,3,2] row_mask:0xf bank_mask:0xf
	v_perm_b32 v192, v190, v188, v202
	v_perm_b32 v193, v191, v189, v202
	v_cndmask_b32_e64 v194, v193, v192, s[98:99]
	s_nop 1
	v_mov_b32_dpp v195, v194 quad_perm:[2,3,0,1] row_mask:0xf bank_mask:0xf
	v_cndmask_b32_e64 v216, v192, v195, s[98:99]
	v_cndmask_b32_e64 v217, v195, v193, s[98:99]
	global_store_dwordx2 v210, v[216:217], s[100:101] offset:2240
	v_add_u32_e32 v210, 0x10000, v209
	v_mul_f32_e32 v198, v138, v74
	v_mul_f32_e32 v199, v142, v75
	v_mul_f32_e32 v200, v146, v76
	v_mul_f32_e32 v201, v150, v77
	v_mul_f32_e32 v198, v204, v198
	v_mul_f32_e32 v199, v204, v199
	v_mul_f32_e32 v200, v204, v200
	v_mul_f32_e32 v201, v204, v201
	v_cvt_pk_bf16_f32 v188, v198, v199
	v_cvt_pk_bf16_f32 v189, v200, v201
	s_nop 0
	v_mov_b32_dpp v190, v188 quad_perm:[1,0,3,2] row_mask:0xf bank_mask:0xf
	v_mov_b32_dpp v191, v189 quad_perm:[1,0,3,2] row_mask:0xf bank_mask:0xf
	v_perm_b32 v192, v190, v188, v202
	v_perm_b32 v193, v191, v189, v202
	v_cndmask_b32_e64 v194, v193, v192, s[98:99]
	s_nop 1
	v_mov_b32_dpp v195, v194 quad_perm:[2,3,0,1] row_mask:0xf bank_mask:0xf
	v_cndmask_b32_e64 v196, v192, v195, s[98:99]
	v_cndmask_b32_e64 v197, v195, v193, s[98:99]
	global_store_dwordx2 v210, v[196:197], s[100:101] offset:2048
	v_mul_f32_e32 v198, v139, v74
	v_mul_f32_e32 v199, v143, v75
	v_mul_f32_e32 v200, v147, v76
	v_mul_f32_e32 v201, v151, v77
	v_mul_f32_e32 v198, v205, v198
	v_mul_f32_e32 v199, v205, v199
	v_mul_f32_e32 v200, v205, v200
	v_mul_f32_e32 v201, v205, v201
	v_cvt_pk_bf16_f32 v188, v198, v199
	v_cvt_pk_bf16_f32 v189, v200, v201
	s_nop 0
	v_mov_b32_dpp v190, v188 quad_perm:[1,0,3,2] row_mask:0xf bank_mask:0xf
	v_mov_b32_dpp v191, v189 quad_perm:[1,0,3,2] row_mask:0xf bank_mask:0xf
	v_perm_b32 v192, v190, v188, v202
	v_perm_b32 v193, v191, v189, v202
	v_cndmask_b32_e64 v194, v193, v192, s[98:99]
	s_nop 1
	v_mov_b32_dpp v195, v194 quad_perm:[2,3,0,1] row_mask:0xf bank_mask:0xf
	v_cndmask_b32_e64 v216, v192, v195, s[98:99]
	v_cndmask_b32_e64 v217, v195, v193, s[98:99]
	global_store_dwordx2 v210, v[216:217], s[100:101] offset:2112
	v_mul_f32_e32 v198, v140, v74
	v_mul_f32_e32 v199, v144, v75
	v_mul_f32_e32 v200, v148, v76
	v_mul_f32_e32 v201, v152, v77
	v_mul_f32_e32 v198, v206, v198
	v_mul_f32_e32 v199, v206, v199
	v_mul_f32_e32 v200, v206, v200
	v_mul_f32_e32 v201, v206, v201
	v_cvt_pk_bf16_f32 v188, v198, v199
	v_cvt_pk_bf16_f32 v189, v200, v201
	s_nop 0
	v_mov_b32_dpp v190, v188 quad_perm:[1,0,3,2] row_mask:0xf bank_mask:0xf
	v_mov_b32_dpp v191, v189 quad_perm:[1,0,3,2] row_mask:0xf bank_mask:0xf
	v_perm_b32 v192, v190, v188, v202
	v_perm_b32 v193, v191, v189, v202
	v_cndmask_b32_e64 v194, v193, v192, s[98:99]
	s_nop 1
	v_mov_b32_dpp v195, v194 quad_perm:[2,3,0,1] row_mask:0xf bank_mask:0xf
	v_cndmask_b32_e64 v196, v192, v195, s[98:99]
	v_cndmask_b32_e64 v197, v195, v193, s[98:99]
	global_store_dwordx2 v210, v[196:197], s[100:101] offset:2176
	v_mul_f32_e32 v198, v141, v74
	v_mul_f32_e32 v199, v145, v75
	v_mul_f32_e32 v200, v149, v76
	v_mul_f32_e32 v201, v153, v77
	v_mul_f32_e32 v198, v207, v198
	v_mul_f32_e32 v199, v207, v199
	v_mul_f32_e32 v200, v207, v200
	v_mul_f32_e32 v201, v207, v201
	v_cvt_pk_bf16_f32 v188, v198, v199
	v_cvt_pk_bf16_f32 v189, v200, v201
	s_nop 0
	v_mov_b32_dpp v190, v188 quad_perm:[1,0,3,2] row_mask:0xf bank_mask:0xf
	v_mov_b32_dpp v191, v189 quad_perm:[1,0,3,2] row_mask:0xf bank_mask:0xf
	v_perm_b32 v192, v190, v188, v202
	v_perm_b32 v193, v191, v189, v202
	v_cndmask_b32_e64 v194, v193, v192, s[98:99]
	s_nop 1
	v_mov_b32_dpp v195, v194 quad_perm:[2,3,0,1] row_mask:0xf bank_mask:0xf
	v_cndmask_b32_e64 v216, v192, v195, s[98:99]
	v_cndmask_b32_e64 v217, v195, v193, s[98:99]
	global_store_dwordx2 v210, v[216:217], s[100:101] offset:2240
	v_add_u32_e32 v210, 0x18000, v209
	v_mul_f32_e32 v198, v154, v78
	v_mul_f32_e32 v199, v176, v79
	v_mul_f32_e32 v200, v180, v80
	v_mul_f32_e32 v201, v184, v81
	v_mul_f32_e32 v198, v204, v198
	v_mul_f32_e32 v199, v204, v199
	v_mul_f32_e32 v200, v204, v200
	v_mul_f32_e32 v201, v204, v201
	v_cvt_pk_bf16_f32 v188, v198, v199
	v_cvt_pk_bf16_f32 v189, v200, v201
	s_nop 0
	v_mov_b32_dpp v190, v188 quad_perm:[1,0,3,2] row_mask:0xf bank_mask:0xf
	v_mov_b32_dpp v191, v189 quad_perm:[1,0,3,2] row_mask:0xf bank_mask:0xf
	v_perm_b32 v192, v190, v188, v202
	v_perm_b32 v193, v191, v189, v202
	v_cndmask_b32_e64 v194, v193, v192, s[98:99]
	s_nop 1
	v_mov_b32_dpp v195, v194 quad_perm:[2,3,0,1] row_mask:0xf bank_mask:0xf
	v_cndmask_b32_e64 v196, v192, v195, s[98:99]
	v_cndmask_b32_e64 v197, v195, v193, s[98:99]
	global_store_dwordx2 v210, v[196:197], s[100:101] offset:2048
	v_mul_f32_e32 v198, v155, v78
	v_mul_f32_e32 v199, v177, v79
	v_mul_f32_e32 v200, v181, v80
	v_mul_f32_e32 v201, v185, v81
	v_mul_f32_e32 v198, v205, v198
	v_mul_f32_e32 v199, v205, v199
	v_mul_f32_e32 v200, v205, v200
	v_mul_f32_e32 v201, v205, v201
	v_cvt_pk_bf16_f32 v188, v198, v199
	v_cvt_pk_bf16_f32 v189, v200, v201
	s_nop 0
	v_mov_b32_dpp v190, v188 quad_perm:[1,0,3,2] row_mask:0xf bank_mask:0xf
	v_mov_b32_dpp v191, v189 quad_perm:[1,0,3,2] row_mask:0xf bank_mask:0xf
	v_perm_b32 v192, v190, v188, v202
	v_perm_b32 v193, v191, v189, v202
	v_cndmask_b32_e64 v194, v193, v192, s[98:99]
	s_nop 1
	v_mov_b32_dpp v195, v194 quad_perm:[2,3,0,1] row_mask:0xf bank_mask:0xf
	v_cndmask_b32_e64 v216, v192, v195, s[98:99]
	v_cndmask_b32_e64 v217, v195, v193, s[98:99]
	global_store_dwordx2 v210, v[216:217], s[100:101] offset:2112
	v_mul_f32_e32 v198, v156, v78
	v_mul_f32_e32 v199, v178, v79
	v_mul_f32_e32 v200, v182, v80
	v_mul_f32_e32 v201, v186, v81
	v_mul_f32_e32 v198, v206, v198
	v_mul_f32_e32 v199, v206, v199
	v_mul_f32_e32 v200, v206, v200
	v_mul_f32_e32 v201, v206, v201
	v_cvt_pk_bf16_f32 v188, v198, v199
	v_cvt_pk_bf16_f32 v189, v200, v201
	s_nop 0
	v_mov_b32_dpp v190, v188 quad_perm:[1,0,3,2] row_mask:0xf bank_mask:0xf
	v_mov_b32_dpp v191, v189 quad_perm:[1,0,3,2] row_mask:0xf bank_mask:0xf
	v_perm_b32 v192, v190, v188, v202
	v_perm_b32 v193, v191, v189, v202
	v_cndmask_b32_e64 v194, v193, v192, s[98:99]
	s_nop 1
	v_mov_b32_dpp v195, v194 quad_perm:[2,3,0,1] row_mask:0xf bank_mask:0xf
	v_cndmask_b32_e64 v196, v192, v195, s[98:99]
	v_cndmask_b32_e64 v197, v195, v193, s[98:99]
	global_store_dwordx2 v210, v[196:197], s[100:101] offset:2176
	v_mul_f32_e32 v198, v157, v78
	v_mul_f32_e32 v199, v179, v79
	v_mul_f32_e32 v200, v183, v80
	v_mul_f32_e32 v201, v187, v81
	v_mul_f32_e32 v198, v207, v198
	v_mul_f32_e32 v199, v207, v199
	v_mul_f32_e32 v200, v207, v200
	v_mul_f32_e32 v201, v207, v201
	v_cvt_pk_bf16_f32 v188, v198, v199
	v_cvt_pk_bf16_f32 v189, v200, v201
	s_nop 0
	v_mov_b32_dpp v190, v188 quad_perm:[1,0,3,2] row_mask:0xf bank_mask:0xf
	v_mov_b32_dpp v191, v189 quad_perm:[1,0,3,2] row_mask:0xf bank_mask:0xf
	v_perm_b32 v192, v190, v188, v202
	v_perm_b32 v193, v191, v189, v202
	v_cndmask_b32_e64 v194, v193, v192, s[98:99]
	s_nop 1
	v_mov_b32_dpp v195, v194 quad_perm:[2,3,0,1] row_mask:0xf bank_mask:0xf
	v_cndmask_b32_e64 v216, v192, v195, s[98:99]
	v_cndmask_b32_e64 v217, v195, v193, s[98:99]
	global_store_dwordx2 v210, v[216:217], s[100:101] offset:2240
	s_cbranch_execnz .LBB0_335
.LBB0_357:
	v_readfirstlane_b32 s96, v158
	v_readfirstlane_b32 s97, v159
	v_and_b32_e32 v254, 63, v162
	v_lshlrev_b32_e32 v254, 4, v254
	s_add_u32 s98, s96, 0x3000
	s_addc_u32 s99, s97, 0
	s_add_u32 s96, s96, 0x1000
	s_addc_u32 s97, s97, 0
	ds_read_b128 v[70:73], v68
	ds_read_b128 v[74:77], v68 offset:32
	v_mov_b32_e32 v67, v34
	v_mov_b32_e32 v80, v18
	v_mov_b32_e32 v66, v50
	s_waitcnt lgkmcnt(1)
	v_rcp_f32_e32 v34, v70
	v_rcp_f32_e32 v18, v71
	v_mov_b32_e32 v81, v2
	v_mov_b32_e32 v2, v19
	v_pk_mul_f32 v[78:79], v[66:67], v[34:35] op_sel_hi:[1,0]
	v_pk_mul_f32 v[80:81], v[80:81], v[34:35] op_sel_hi:[1,0]
	global_store_dwordx4 v254, v[78:81], s[96:97] offset:-4096 nt
	v_mov_b32_e32 v34, v51
	s_nop 0
	v_pk_mul_f32 v[80:81], v[2:3], v[18:19] op_sel_hi:[1,0]
	v_rcp_f32_e32 v2, v72
	v_pk_mul_f32 v[78:79], v[34:35], v[18:19] op_sel_hi:[1,0]
	v_mov_b32_e32 v18, v52
	v_mov_b32_e32 v19, v36
	v_pk_mul_f32 v[70:71], v[18:19], v[2:3] op_sel_hi:[1,0]
	v_mov_b32_e32 v18, v20
	v_rcp_f32_e32 v20, v73
	v_mov_b32_e32 v19, v4
	v_pk_mul_f32 v[72:73], v[18:19], v[2:3] op_sel_hi:[1,0]
	v_mov_b32_e32 v36, v53
	v_mov_b32_e32 v4, v21
	s_waitcnt lgkmcnt(0)
	v_rcp_f32_e32 v18, v74
	v_pk_mul_f32 v[2:3], v[36:37], v[20:21] op_sel_hi:[1,0]
	v_pk_mul_f32 v[4:5], v[4:5], v[20:21] op_sel_hi:[1,0]
	v_rcp_f32_e32 v20, v75
	global_store_dwordx4 v254, v[2:5], s[96:97] offset:-1024 nt
	global_store_dwordx4 v254, v[78:81], s[96:97] offset:-3072 nt
	global_store_dwordx4 v254, v[70:73], s[96:97] offset:-2048 nt
	v_mov_b32_e32 v2, v54
	v_mov_b32_e32 v3, v38
	v_mov_b32_e32 v4, v22
	v_mov_b32_e32 v5, v6
	v_pk_mul_f32 v[2:3], v[2:3], v[18:19] op_sel_hi:[1,0]
	v_pk_mul_f32 v[4:5], v[4:5], v[18:19] op_sel_hi:[1,0]
	v_mov_b32_e32 v6, v23
	global_store_dwordx4 v254, v[2:5], s[96:97] offset:0 nt
	v_mov_b32_e32 v38, v55
	v_rcp_f32_e32 v18, v77
	v_pk_mul_f32 v[4:5], v[6:7], v[20:21] op_sel_hi:[1,0]
	v_rcp_f32_e32 v6, v76
	v_pk_mul_f32 v[2:3], v[38:39], v[20:21] op_sel_hi:[1,0]
	global_store_dwordx4 v254, v[2:5], s[96:97] offset:1024 nt
	s_nop 1
	v_mov_b32_e32 v2, v56
	v_mov_b32_e32 v3, v40
	v_mov_b32_e32 v4, v24
	v_mov_b32_e32 v5, v8
	v_pk_mul_f32 v[2:3], v[2:3], v[6:7] op_sel_hi:[1,0]
	v_pk_mul_f32 v[4:5], v[4:5], v[6:7] op_sel_hi:[1,0]
	global_store_dwordx4 v254, v[2:5], s[96:97] offset:2048 nt
	ds_read_b128 v[2:5], v68 offset:64
	v_mov_b32_e32 v40, v57
	v_mov_b32_e32 v8, v25
	v_pk_mul_f32 v[6:7], v[40:41], v[18:19] op_sel_hi:[1,0]
	v_pk_mul_f32 v[8:9], v[8:9], v[18:19] op_sel_hi:[1,0]
	ds_read_b128 v[18:21], v68 offset:96
	s_waitcnt lgkmcnt(1)
	v_rcp_f32_e32 v2, v2
	v_rcp_f32_e32 v22, v3
	global_store_dwordx4 v254, v[6:9], s[96:97] offset:3072 nt
	v_rcp_f32_e32 v4, v4
	s_nop 0
	v_mov_b32_e32 v6, v58
	v_mov_b32_e32 v7, v42
	v_mov_b32_e32 v8, v26
	v_mov_b32_e32 v9, v10
	v_pk_mul_f32 v[6:7], v[6:7], v[2:3] op_sel_hi:[1,0]
	v_pk_mul_f32 v[8:9], v[8:9], v[2:3] op_sel_hi:[1,0]
	v_mov_b32_e32 v42, v59
	v_mov_b32_e32 v10, v27
	global_store_dwordx4 v254, v[6:9], s[98:99] offset:-4096 nt
	v_mov_b32_e32 v2, v60
	v_mov_b32_e32 v3, v44
	v_pk_mul_f32 v[6:7], v[42:43], v[22:23] op_sel_hi:[1,0]
	v_pk_mul_f32 v[8:9], v[10:11], v[22:23] op_sel_hi:[1,0]
	global_store_dwordx4 v254, v[6:9], s[98:99] offset:-3072 nt
	v_pk_mul_f32 v[2:3], v[2:3], v[4:5] op_sel_hi:[1,0]
	v_mov_b32_e32 v44, v61
	v_rcp_f32_e32 v8, v5
	v_mov_b32_e32 v6, v28
	v_mov_b32_e32 v7, v12
	v_pk_mul_f32 v[4:5], v[6:7], v[4:5] op_sel_hi:[1,0]
	v_mov_b32_e32 v12, v29
	s_waitcnt lgkmcnt(0)
	v_rcp_f32_e32 v6, v18
	global_store_dwordx4 v254, v[2:5], s[98:99] offset:-2048 nt
	s_nop 1
	v_pk_mul_f32 v[2:3], v[44:45], v[8:9] op_sel_hi:[1,0]
	v_pk_mul_f32 v[4:5], v[12:13], v[8:9] op_sel_hi:[1,0]
	v_rcp_f32_e32 v8, v19
	global_store_dwordx4 v254, v[2:5], s[98:99] offset:-1024 nt
	s_nop 1
	v_mov_b32_e32 v2, v62
	v_mov_b32_e32 v3, v46
	v_mov_b32_e32 v4, v30
	v_mov_b32_e32 v5, v14
	v_pk_mul_f32 v[2:3], v[2:3], v[6:7] op_sel_hi:[1,0]
	v_pk_mul_f32 v[4:5], v[4:5], v[6:7] op_sel_hi:[1,0]
	v_mov_b32_e32 v46, v63
	v_mov_b32_e32 v14, v31
	v_rcp_f32_e32 v6, v20
	global_store_dwordx4 v254, v[2:5], s[98:99] offset:0 nt
	s_nop 1
	v_pk_mul_f32 v[2:3], v[46:47], v[8:9] op_sel_hi:[1,0]
	v_pk_mul_f32 v[4:5], v[14:15], v[8:9] op_sel_hi:[1,0]
	v_rcp_f32_e32 v8, v21
	global_store_dwordx4 v254, v[2:5], s[98:99] offset:1024 nt
	s_nop 1
	v_mov_b32_e32 v2, v64
	v_mov_b32_e32 v3, v48
	v_mov_b32_e32 v4, v32
	v_mov_b32_e32 v5, v16
	v_pk_mul_f32 v[2:3], v[2:3], v[6:7] op_sel_hi:[1,0]
	v_pk_mul_f32 v[4:5], v[4:5], v[6:7] op_sel_hi:[1,0]
	v_mov_b32_e32 v48, v65
	v_mov_b32_e32 v16, v33
	global_store_dwordx4 v254, v[2:5], s[98:99] offset:2048 nt
	s_nop 1
	v_pk_mul_f32 v[2:3], v[48:49], v[8:9] op_sel_hi:[1,0]
	v_pk_mul_f32 v[4:5], v[16:17], v[8:9] op_sel_hi:[1,0]
	global_store_dwordx4 v254, v[2:5], s[98:99] offset:3072 nt
	s_branch .LBB0_335
